# w_in GEMM epilogue fast path extended to the c_q tile column (scale, pack, store, row sum-of-squares via permlane swaps, one atomic per row group)
# speedup vs baseline: 1.0110x; 1.0033x over previous
.LBB0_295:
	s_cmp_gt_i32 s4, 2
	s_cbranch_scc1 .Lwin_slow
	v_and_b32_e32 v177, 15, v192
	v_bfe_u32 v162, v192, 6, 2
	v_bfe_u32 v163, v192, 4, 2
	v_ashrrev_i32_e32 v80, 2, v192
	v_and_b32_e32 v80, 0xffffffc0, v80
	v_lshl_or_b32 v164, s52, 8, v177
	v_add_u32_e32 v164, v164, v80
	v_ashrrev_i32_e32 v165, 31, v164
	v_lshl_add_u64 v[166:167], v[164:165], 2, s[90:91]
	s_mov_b64 vcc, 0x20000
	s_nop 0
	v_lshl_add_u64 v[166:167], v[166:167], 0, vcc
	global_load_dword v214, v[166:167], off
	global_load_dword v215, v[166:167], off offset:64
	global_load_dword v216, v[166:167], off offset:128
	global_load_dword v217, v[166:167], off offset:192
	global_load_dword v218, v[166:167], off offset:512
	global_load_dword v219, v[166:167], off offset:576
	global_load_dword v220, v[166:167], off offset:640
	global_load_dword v221, v[166:167], off offset:704
	s_lshl_b32 s43, s4, 8
	v_lshlrev_b32_e32 v168, 5, v162
	v_lshlrev_b32_e32 v169, 3, v163
	v_or3_b32 v168, v168, s43, v169
	s_cmp_eq_u32 s4, 2
	s_cbranch_scc1 .Lwin_q
	v_ashrrev_i32_e32 v170, 4, v168
	v_lshlrev_b32_e32 v170, 10, v170
	v_ashrrev_i32_e32 v171, 5, v164
	v_add_u32_e32 v170, v170, v171
	v_mul_u32_u24_e32 v170, 0x500, v170
	v_lshlrev_b32_e32 v171, 5, v177
	v_and_b32_e32 v169, 8, v169
	v_lshlrev_b32_e32 v169, 1, v169
	v_add3_u32 v170, v170, v171, v169
	v_mov_b32_e32 v171, v81
	v_lshl_add_u64 v[170:171], v[170:171], 0, s[62:63]
	s_mov_b64 vcc, 0x1400
	s_nop 0
	v_lshl_add_u64 v[172:173], v[170:171], 0, vcc
	s_mov_b64 vcc, 0xa00000
	s_nop 0
	v_lshl_add_u64 v[174:175], v[170:171], 0, vcc
	v_lshl_add_u64 v[178:179], v[172:173], 0, vcc
	s_waitcnt vmcnt(7)
	v_fmamk_f32 v180, v214, 0x3a800000, v194
	v_rsq_f32_e32 v180, v180
	s_nop 0
	v_pk_mul_f32 v[126:127], v[126:127], v[180:181] op_sel_hi:[1,0]
	v_pk_mul_f32 v[128:129], v[128:129], v[180:181] op_sel_hi:[1,0]
	v_pk_mul_f32 v[122:123], v[122:123], v[180:181] op_sel_hi:[1,0]
	v_pk_mul_f32 v[124:125], v[124:125], v[180:181] op_sel_hi:[1,0]
	v_cvt_pk_bf16_f32 v126, v126, v127
	v_cvt_pk_bf16_f32 v127, v128, v129
	v_cvt_pk_bf16_f32 v128, v122, v123
	v_cvt_pk_bf16_f32 v129, v124, v125
	global_store_dwordx4 v[170:171], v[126:129], off
	v_pk_mul_f32 v[118:119], v[118:119], v[180:181] op_sel_hi:[1,0]
	v_pk_mul_f32 v[120:121], v[120:121], v[180:181] op_sel_hi:[1,0]
	v_pk_mul_f32 v[114:115], v[114:115], v[180:181] op_sel_hi:[1,0]
	v_pk_mul_f32 v[116:117], v[116:117], v[180:181] op_sel_hi:[1,0]
	v_cvt_pk_bf16_f32 v118, v118, v119
	v_cvt_pk_bf16_f32 v119, v120, v121
	v_cvt_pk_bf16_f32 v120, v114, v115
	v_cvt_pk_bf16_f32 v121, v116, v117
	global_store_dwordx4 v[174:175], v[118:121], off
	s_waitcnt vmcnt(8)
	v_fmamk_f32 v180, v215, 0x3a800000, v194
	v_rsq_f32_e32 v180, v180
	s_nop 0
	v_pk_mul_f32 v[110:111], v[110:111], v[180:181] op_sel_hi:[1,0]
	v_pk_mul_f32 v[112:113], v[112:113], v[180:181] op_sel_hi:[1,0]
	v_pk_mul_f32 v[106:107], v[106:107], v[180:181] op_sel_hi:[1,0]
	v_pk_mul_f32 v[108:109], v[108:109], v[180:181] op_sel_hi:[1,0]
	v_cvt_pk_bf16_f32 v110, v110, v111
	v_cvt_pk_bf16_f32 v111, v112, v113
	v_cvt_pk_bf16_f32 v112, v106, v107
	v_cvt_pk_bf16_f32 v113, v108, v109
	global_store_dwordx4 v[170:171], v[110:113], off offset:512
	v_pk_mul_f32 v[102:103], v[102:103], v[180:181] op_sel_hi:[1,0]
	v_pk_mul_f32 v[104:105], v[104:105], v[180:181] op_sel_hi:[1,0]
	v_pk_mul_f32 v[98:99], v[98:99], v[180:181] op_sel_hi:[1,0]
	v_pk_mul_f32 v[100:101], v[100:101], v[180:181] op_sel_hi:[1,0]
	v_cvt_pk_bf16_f32 v102, v102, v103
	v_cvt_pk_bf16_f32 v103, v104, v105
	v_cvt_pk_bf16_f32 v104, v98, v99
	v_cvt_pk_bf16_f32 v105, v100, v101
	global_store_dwordx4 v[174:175], v[102:105], off offset:512
	s_waitcnt vmcnt(9)
	v_fmamk_f32 v180, v216, 0x3a800000, v194
	v_rsq_f32_e32 v180, v180
	s_nop 0
	v_pk_mul_f32 v[94:95], v[94:95], v[180:181] op_sel_hi:[1,0]
	v_pk_mul_f32 v[96:97], v[96:97], v[180:181] op_sel_hi:[1,0]
	v_pk_mul_f32 v[90:91], v[90:91], v[180:181] op_sel_hi:[1,0]
	v_pk_mul_f32 v[92:93], v[92:93], v[180:181] op_sel_hi:[1,0]
	v_cvt_pk_bf16_f32 v94, v94, v95
	v_cvt_pk_bf16_f32 v95, v96, v97
	v_cvt_pk_bf16_f32 v96, v90, v91
	v_cvt_pk_bf16_f32 v97, v92, v93
	global_store_dwordx4 v[170:171], v[94:97], off offset:1280
	v_pk_mul_f32 v[86:87], v[86:87], v[180:181] op_sel_hi:[1,0]
	v_pk_mul_f32 v[88:89], v[88:89], v[180:181] op_sel_hi:[1,0]
	v_pk_mul_f32 v[82:83], v[82:83], v[180:181] op_sel_hi:[1,0]
	v_pk_mul_f32 v[84:85], v[84:85], v[180:181] op_sel_hi:[1,0]
	v_cvt_pk_bf16_f32 v86, v86, v87
	v_cvt_pk_bf16_f32 v87, v88, v89
	v_cvt_pk_bf16_f32 v88, v82, v83
	v_cvt_pk_bf16_f32 v89, v84, v85
	global_store_dwordx4 v[174:175], v[86:89], off offset:1280
	s_waitcnt vmcnt(10)
	v_fmamk_f32 v180, v217, 0x3a800000, v194
	v_rsq_f32_e32 v180, v180
	s_nop 0
	v_pk_mul_f32 v[76:77], v[76:77], v[180:181] op_sel_hi:[1,0]
	v_pk_mul_f32 v[78:79], v[78:79], v[180:181] op_sel_hi:[1,0]
	v_pk_mul_f32 v[72:73], v[72:73], v[180:181] op_sel_hi:[1,0]
	v_pk_mul_f32 v[74:75], v[74:75], v[180:181] op_sel_hi:[1,0]
	v_cvt_pk_bf16_f32 v76, v76, v77
	v_cvt_pk_bf16_f32 v77, v78, v79
	v_cvt_pk_bf16_f32 v78, v72, v73
	v_cvt_pk_bf16_f32 v79, v74, v75
	global_store_dwordx4 v[170:171], v[76:79], off offset:1792
	v_pk_mul_f32 v[68:69], v[68:69], v[180:181] op_sel_hi:[1,0]
	v_pk_mul_f32 v[70:71], v[70:71], v[180:181] op_sel_hi:[1,0]
	v_pk_mul_f32 v[64:65], v[64:65], v[180:181] op_sel_hi:[1,0]
	v_pk_mul_f32 v[66:67], v[66:67], v[180:181] op_sel_hi:[1,0]
	v_cvt_pk_bf16_f32 v68, v68, v69
	v_cvt_pk_bf16_f32 v69, v70, v71
	v_cvt_pk_bf16_f32 v70, v64, v65
	v_cvt_pk_bf16_f32 v71, v66, v67
	global_store_dwordx4 v[174:175], v[68:71], off offset:1792
	s_waitcnt vmcnt(11)
	v_fmamk_f32 v180, v218, 0x3a800000, v194
	v_rsq_f32_e32 v180, v180
	s_nop 0
	v_pk_mul_f32 v[60:61], v[60:61], v[180:181] op_sel_hi:[1,0]
	v_pk_mul_f32 v[62:63], v[62:63], v[180:181] op_sel_hi:[1,0]
	v_pk_mul_f32 v[56:57], v[56:57], v[180:181] op_sel_hi:[1,0]
	v_pk_mul_f32 v[58:59], v[58:59], v[180:181] op_sel_hi:[1,0]
	v_cvt_pk_bf16_f32 v60, v60, v61
	v_cvt_pk_bf16_f32 v61, v62, v63
	v_cvt_pk_bf16_f32 v62, v56, v57
	v_cvt_pk_bf16_f32 v63, v58, v59
	global_store_dwordx4 v[172:173], v[60:63], off
	v_pk_mul_f32 v[52:53], v[52:53], v[180:181] op_sel_hi:[1,0]
	v_pk_mul_f32 v[54:55], v[54:55], v[180:181] op_sel_hi:[1,0]
	v_pk_mul_f32 v[48:49], v[48:49], v[180:181] op_sel_hi:[1,0]
	v_pk_mul_f32 v[50:51], v[50:51], v[180:181] op_sel_hi:[1,0]
	v_cvt_pk_bf16_f32 v52, v52, v53
	v_cvt_pk_bf16_f32 v53, v54, v55
	v_cvt_pk_bf16_f32 v54, v48, v49
	v_cvt_pk_bf16_f32 v55, v50, v51
	global_store_dwordx4 v[178:179], v[52:55], off
	s_waitcnt vmcnt(12)
	v_fmamk_f32 v180, v219, 0x3a800000, v194
	v_rsq_f32_e32 v180, v180
	s_nop 0
	v_pk_mul_f32 v[44:45], v[44:45], v[180:181] op_sel_hi:[1,0]
	v_pk_mul_f32 v[46:47], v[46:47], v[180:181] op_sel_hi:[1,0]
	v_pk_mul_f32 v[40:41], v[40:41], v[180:181] op_sel_hi:[1,0]
	v_pk_mul_f32 v[42:43], v[42:43], v[180:181] op_sel_hi:[1,0]
	v_cvt_pk_bf16_f32 v44, v44, v45
	v_cvt_pk_bf16_f32 v45, v46, v47
	v_cvt_pk_bf16_f32 v46, v40, v41
	v_cvt_pk_bf16_f32 v47, v42, v43
	global_store_dwordx4 v[172:173], v[44:47], off offset:512
	v_pk_mul_f32 v[36:37], v[36:37], v[180:181] op_sel_hi:[1,0]
	v_pk_mul_f32 v[38:39], v[38:39], v[180:181] op_sel_hi:[1,0]
	v_pk_mul_f32 v[32:33], v[32:33], v[180:181] op_sel_hi:[1,0]
	v_pk_mul_f32 v[34:35], v[34:35], v[180:181] op_sel_hi:[1,0]
	v_cvt_pk_bf16_f32 v36, v36, v37
	v_cvt_pk_bf16_f32 v37, v38, v39
	v_cvt_pk_bf16_f32 v38, v32, v33
	v_cvt_pk_bf16_f32 v39, v34, v35
	global_store_dwordx4 v[178:179], v[36:39], off offset:512
	s_waitcnt vmcnt(13)
	v_fmamk_f32 v180, v220, 0x3a800000, v194
	v_rsq_f32_e32 v180, v180
	s_nop 0
	v_pk_mul_f32 v[28:29], v[28:29], v[180:181] op_sel_hi:[1,0]
	v_pk_mul_f32 v[30:31], v[30:31], v[180:181] op_sel_hi:[1,0]
	v_pk_mul_f32 v[24:25], v[24:25], v[180:181] op_sel_hi:[1,0]
	v_pk_mul_f32 v[26:27], v[26:27], v[180:181] op_sel_hi:[1,0]
	v_cvt_pk_bf16_f32 v28, v28, v29
	v_cvt_pk_bf16_f32 v29, v30, v31
	v_cvt_pk_bf16_f32 v30, v24, v25
	v_cvt_pk_bf16_f32 v31, v26, v27
	global_store_dwordx4 v[172:173], v[28:31], off offset:1280
	v_pk_mul_f32 v[20:21], v[20:21], v[180:181] op_sel_hi:[1,0]
	v_pk_mul_f32 v[22:23], v[22:23], v[180:181] op_sel_hi:[1,0]
	v_pk_mul_f32 v[16:17], v[16:17], v[180:181] op_sel_hi:[1,0]
	v_pk_mul_f32 v[18:19], v[18:19], v[180:181] op_sel_hi:[1,0]
	v_cvt_pk_bf16_f32 v20, v20, v21
	v_cvt_pk_bf16_f32 v21, v22, v23
	v_cvt_pk_bf16_f32 v22, v16, v17
	v_cvt_pk_bf16_f32 v23, v18, v19
	global_store_dwordx4 v[178:179], v[20:23], off offset:1280
	s_waitcnt vmcnt(14)
	v_fmamk_f32 v180, v221, 0x3a800000, v194
	v_rsq_f32_e32 v180, v180
	s_nop 0
	v_pk_mul_f32 v[12:13], v[12:13], v[180:181] op_sel_hi:[1,0]
	v_pk_mul_f32 v[14:15], v[14:15], v[180:181] op_sel_hi:[1,0]
	v_pk_mul_f32 v[8:9], v[8:9], v[180:181] op_sel_hi:[1,0]
	v_pk_mul_f32 v[10:11], v[10:11], v[180:181] op_sel_hi:[1,0]
	v_cvt_pk_bf16_f32 v12, v12, v13
	v_cvt_pk_bf16_f32 v13, v14, v15
	v_cvt_pk_bf16_f32 v14, v8, v9
	v_cvt_pk_bf16_f32 v15, v10, v11
	global_store_dwordx4 v[172:173], v[12:15], off offset:1792
	v_pk_mul_f32 v[4:5], v[4:5], v[180:181] op_sel_hi:[1,0]
	v_pk_mul_f32 v[6:7], v[6:7], v[180:181] op_sel_hi:[1,0]
	v_pk_mul_f32 v[0:1], v[0:1], v[180:181] op_sel_hi:[1,0]
	v_pk_mul_f32 v[2:3], v[2:3], v[180:181] op_sel_hi:[1,0]
	v_cvt_pk_bf16_f32 v4, v4, v5
	v_cvt_pk_bf16_f32 v5, v6, v7
	v_cvt_pk_bf16_f32 v6, v0, v1
	v_cvt_pk_bf16_f32 v7, v2, v3
	global_store_dwordx4 v[178:179], v[4:7], off offset:1792
	s_mov_b64 s[48:49], exec
	s_branch .LBB0_612
.Lwin_q:
	v_mad_i64_i32 v[170:171], s[46:47], v164, s29, 0
	v_lshl_add_u64 v[170:171], s[90:91], 0, v[170:171]
	v_mov_b32_e32 v169, v81
	v_lshl_add_u64 v[170:171], v[168:169], 1, v[170:171]
	s_mov_b64 vcc, 0x1488f000
	s_nop 0
	v_lshl_add_u64 v[170:171], v[170:171], 0, vcc
	v_lshl_add_u64 v[172:173], v[164:165], 2, s[90:91]
	s_mov_b64 vcc, 0x80000
	s_nop 0
	v_lshl_add_u64 v[172:173], v[172:173], 0, vcc
	v_cmp_eq_u32_e64 s[46:47], 0, v163
	s_waitcnt vmcnt(7)
	v_fmamk_f32 v180, v214, 0x3a800000, v194
	v_rsq_f32_e32 v180, v180
	s_nop 0
	v_pk_mul_f32 v[126:127], v[126:127], v[180:181] op_sel_hi:[1,0]
	v_pk_mul_f32 v[128:129], v[128:129], v[180:181] op_sel_hi:[1,0]
	v_pk_mul_f32 v[122:123], v[122:123], v[180:181] op_sel_hi:[1,0]
	v_pk_mul_f32 v[124:125], v[124:125], v[180:181] op_sel_hi:[1,0]
	v_pk_mul_f32 v[182:183], v[126:127], v[126:127]
	v_pk_fma_f32 v[182:183], v[128:129], v[128:129], v[182:183]
	v_pk_fma_f32 v[182:183], v[122:123], v[122:123], v[182:183]
	v_pk_fma_f32 v[182:183], v[124:125], v[124:125], v[182:183]
	v_cvt_pk_bf16_f32 v126, v126, v127
	v_cvt_pk_bf16_f32 v127, v128, v129
	v_cvt_pk_bf16_f32 v128, v122, v123
	v_cvt_pk_bf16_f32 v129, v124, v125
	global_store_dwordx4 v[170:171], v[126:129], off offset:3072
	v_pk_mul_f32 v[118:119], v[118:119], v[180:181] op_sel_hi:[1,0]
	v_pk_mul_f32 v[120:121], v[120:121], v[180:181] op_sel_hi:[1,0]
	v_pk_mul_f32 v[114:115], v[114:115], v[180:181] op_sel_hi:[1,0]
	v_pk_mul_f32 v[116:117], v[116:117], v[180:181] op_sel_hi:[1,0]
	v_pk_fma_f32 v[182:183], v[118:119], v[118:119], v[182:183]
	v_pk_fma_f32 v[182:183], v[120:121], v[120:121], v[182:183]
	v_pk_fma_f32 v[182:183], v[114:115], v[114:115], v[182:183]
	v_pk_fma_f32 v[182:183], v[116:117], v[116:117], v[182:183]
	v_cvt_pk_bf16_f32 v118, v118, v119
	v_cvt_pk_bf16_f32 v119, v120, v121
	v_cvt_pk_bf16_f32 v120, v114, v115
	v_cvt_pk_bf16_f32 v121, v116, v117
	global_store_dwordx4 v[170:171], v[118:121], off offset:3328
	v_add_f32_e32 v184, v182, v183
	v_mov_b32_e32 v185, v184
	s_nop 1
	v_permlane32_swap_b32 v185, v184
	s_nop 1
	v_add_f32_e32 v184, v184, v185
	v_mov_b32_e32 v185, v184
	s_nop 1
	v_permlane16_swap_b32 v185, v184
	s_nop 1
	v_add_f32_e32 v184, v184, v185
	s_mov_b64 exec, s[46:47]
	global_atomic_add_f32 v[172:173], v184, off
	s_mov_b64 exec, -1
	s_mov_b64 vcc, 0x3000
	s_nop 0
	v_lshl_add_u64 v[170:171], v[170:171], 0, vcc
	s_waitcnt vmcnt(9)
	v_fmamk_f32 v180, v215, 0x3a800000, v194
	v_rsq_f32_e32 v180, v180
	s_nop 0
	v_pk_mul_f32 v[110:111], v[110:111], v[180:181] op_sel_hi:[1,0]
	v_pk_mul_f32 v[112:113], v[112:113], v[180:181] op_sel_hi:[1,0]
	v_pk_mul_f32 v[106:107], v[106:107], v[180:181] op_sel_hi:[1,0]
	v_pk_mul_f32 v[108:109], v[108:109], v[180:181] op_sel_hi:[1,0]
	v_pk_mul_f32 v[182:183], v[110:111], v[110:111]
	v_pk_fma_f32 v[182:183], v[112:113], v[112:113], v[182:183]
	v_pk_fma_f32 v[182:183], v[106:107], v[106:107], v[182:183]
	v_pk_fma_f32 v[182:183], v[108:109], v[108:109], v[182:183]
	v_cvt_pk_bf16_f32 v110, v110, v111
	v_cvt_pk_bf16_f32 v111, v112, v113
	v_cvt_pk_bf16_f32 v112, v106, v107
	v_cvt_pk_bf16_f32 v113, v108, v109
	global_store_dwordx4 v[170:171], v[110:113], off offset:3072
	v_pk_mul_f32 v[102:103], v[102:103], v[180:181] op_sel_hi:[1,0]
	v_pk_mul_f32 v[104:105], v[104:105], v[180:181] op_sel_hi:[1,0]
	v_pk_mul_f32 v[98:99], v[98:99], v[180:181] op_sel_hi:[1,0]
	v_pk_mul_f32 v[100:101], v[100:101], v[180:181] op_sel_hi:[1,0]
	v_pk_fma_f32 v[182:183], v[102:103], v[102:103], v[182:183]
	v_pk_fma_f32 v[182:183], v[104:105], v[104:105], v[182:183]
	v_pk_fma_f32 v[182:183], v[98:99], v[98:99], v[182:183]
	v_pk_fma_f32 v[182:183], v[100:101], v[100:101], v[182:183]
	v_cvt_pk_bf16_f32 v102, v102, v103
	v_cvt_pk_bf16_f32 v103, v104, v105
	v_cvt_pk_bf16_f32 v104, v98, v99
	v_cvt_pk_bf16_f32 v105, v100, v101
	global_store_dwordx4 v[170:171], v[102:105], off offset:3328
	v_add_f32_e32 v184, v182, v183
	v_mov_b32_e32 v185, v184
	s_nop 1
	v_permlane32_swap_b32 v185, v184
	s_nop 1
	v_add_f32_e32 v184, v184, v185
	v_mov_b32_e32 v185, v184
	s_nop 1
	v_permlane16_swap_b32 v185, v184
	s_nop 1
	v_add_f32_e32 v184, v184, v185
	s_mov_b64 exec, s[46:47]
	global_atomic_add_f32 v[172:173], v184, off offset:64
	s_mov_b64 exec, -1
	s_mov_b64 vcc, 0x3000
	s_nop 0
	v_lshl_add_u64 v[170:171], v[170:171], 0, vcc
	s_waitcnt vmcnt(11)
	v_fmamk_f32 v180, v216, 0x3a800000, v194
	v_rsq_f32_e32 v180, v180
	s_nop 0
	v_pk_mul_f32 v[94:95], v[94:95], v[180:181] op_sel_hi:[1,0]
	v_pk_mul_f32 v[96:97], v[96:97], v[180:181] op_sel_hi:[1,0]
	v_pk_mul_f32 v[90:91], v[90:91], v[180:181] op_sel_hi:[1,0]
	v_pk_mul_f32 v[92:93], v[92:93], v[180:181] op_sel_hi:[1,0]
	v_pk_mul_f32 v[182:183], v[94:95], v[94:95]
	v_pk_fma_f32 v[182:183], v[96:97], v[96:97], v[182:183]
	v_pk_fma_f32 v[182:183], v[90:91], v[90:91], v[182:183]
	v_pk_fma_f32 v[182:183], v[92:93], v[92:93], v[182:183]
	v_cvt_pk_bf16_f32 v94, v94, v95
	v_cvt_pk_bf16_f32 v95, v96, v97
	v_cvt_pk_bf16_f32 v96, v90, v91
	v_cvt_pk_bf16_f32 v97, v92, v93
	global_store_dwordx4 v[170:171], v[94:97], off offset:3072
	v_pk_mul_f32 v[86:87], v[86:87], v[180:181] op_sel_hi:[1,0]
	v_pk_mul_f32 v[88:89], v[88:89], v[180:181] op_sel_hi:[1,0]
	v_pk_mul_f32 v[82:83], v[82:83], v[180:181] op_sel_hi:[1,0]
	v_pk_mul_f32 v[84:85], v[84:85], v[180:181] op_sel_hi:[1,0]
	v_pk_fma_f32 v[182:183], v[86:87], v[86:87], v[182:183]
	v_pk_fma_f32 v[182:183], v[88:89], v[88:89], v[182:183]
	v_pk_fma_f32 v[182:183], v[82:83], v[82:83], v[182:183]
	v_pk_fma_f32 v[182:183], v[84:85], v[84:85], v[182:183]
	v_cvt_pk_bf16_f32 v86, v86, v87
	v_cvt_pk_bf16_f32 v87, v88, v89
	v_cvt_pk_bf16_f32 v88, v82, v83
	v_cvt_pk_bf16_f32 v89, v84, v85
	global_store_dwordx4 v[170:171], v[86:89], off offset:3328
	v_add_f32_e32 v184, v182, v183
	v_mov_b32_e32 v185, v184
	s_nop 1
	v_permlane32_swap_b32 v185, v184
	s_nop 1
	v_add_f32_e32 v184, v184, v185
	v_mov_b32_e32 v185, v184
	s_nop 1
	v_permlane16_swap_b32 v185, v184
	s_nop 1
	v_add_f32_e32 v184, v184, v185
	s_mov_b64 exec, s[46:47]
	global_atomic_add_f32 v[172:173], v184, off offset:128
	s_mov_b64 exec, -1
	s_mov_b64 vcc, 0x3000
	s_nop 0
	v_lshl_add_u64 v[170:171], v[170:171], 0, vcc
	s_waitcnt vmcnt(13)
	v_fmamk_f32 v180, v217, 0x3a800000, v194
	v_rsq_f32_e32 v180, v180
	s_nop 0
	v_pk_mul_f32 v[76:77], v[76:77], v[180:181] op_sel_hi:[1,0]
	v_pk_mul_f32 v[78:79], v[78:79], v[180:181] op_sel_hi:[1,0]
	v_pk_mul_f32 v[72:73], v[72:73], v[180:181] op_sel_hi:[1,0]
	v_pk_mul_f32 v[74:75], v[74:75], v[180:181] op_sel_hi:[1,0]
	v_pk_mul_f32 v[182:183], v[76:77], v[76:77]
	v_pk_fma_f32 v[182:183], v[78:79], v[78:79], v[182:183]
	v_pk_fma_f32 v[182:183], v[72:73], v[72:73], v[182:183]
	v_pk_fma_f32 v[182:183], v[74:75], v[74:75], v[182:183]
	v_cvt_pk_bf16_f32 v76, v76, v77
	v_cvt_pk_bf16_f32 v77, v78, v79
	v_cvt_pk_bf16_f32 v78, v72, v73
	v_cvt_pk_bf16_f32 v79, v74, v75
	global_store_dwordx4 v[170:171], v[76:79], off offset:3072
	v_pk_mul_f32 v[68:69], v[68:69], v[180:181] op_sel_hi:[1,0]
	v_pk_mul_f32 v[70:71], v[70:71], v[180:181] op_sel_hi:[1,0]
	v_pk_mul_f32 v[64:65], v[64:65], v[180:181] op_sel_hi:[1,0]
	v_pk_mul_f32 v[66:67], v[66:67], v[180:181] op_sel_hi:[1,0]
	v_pk_fma_f32 v[182:183], v[68:69], v[68:69], v[182:183]
	v_pk_fma_f32 v[182:183], v[70:71], v[70:71], v[182:183]
	v_pk_fma_f32 v[182:183], v[64:65], v[64:65], v[182:183]
	v_pk_fma_f32 v[182:183], v[66:67], v[66:67], v[182:183]
	v_cvt_pk_bf16_f32 v68, v68, v69
	v_cvt_pk_bf16_f32 v69, v70, v71
	v_cvt_pk_bf16_f32 v70, v64, v65
	v_cvt_pk_bf16_f32 v71, v66, v67
	global_store_dwordx4 v[170:171], v[68:71], off offset:3328
	v_add_f32_e32 v184, v182, v183
	v_mov_b32_e32 v185, v184
	s_nop 1
	v_permlane32_swap_b32 v185, v184
	s_nop 1
	v_add_f32_e32 v184, v184, v185
	v_mov_b32_e32 v185, v184
	s_nop 1
	v_permlane16_swap_b32 v185, v184
	s_nop 1
	v_add_f32_e32 v184, v184, v185
	s_mov_b64 exec, s[46:47]
	global_atomic_add_f32 v[172:173], v184, off offset:192
	s_mov_b64 exec, -1
	s_mov_b64 vcc, 0xf000
	s_nop 0
	v_lshl_add_u64 v[170:171], v[170:171], 0, vcc
	s_waitcnt vmcnt(15)
	v_fmamk_f32 v180, v218, 0x3a800000, v194
	v_rsq_f32_e32 v180, v180
	s_nop 0
	v_pk_mul_f32 v[60:61], v[60:61], v[180:181] op_sel_hi:[1,0]
	v_pk_mul_f32 v[62:63], v[62:63], v[180:181] op_sel_hi:[1,0]
	v_pk_mul_f32 v[56:57], v[56:57], v[180:181] op_sel_hi:[1,0]
	v_pk_mul_f32 v[58:59], v[58:59], v[180:181] op_sel_hi:[1,0]
	v_pk_mul_f32 v[182:183], v[60:61], v[60:61]
	v_pk_fma_f32 v[182:183], v[62:63], v[62:63], v[182:183]
	v_pk_fma_f32 v[182:183], v[56:57], v[56:57], v[182:183]
	v_pk_fma_f32 v[182:183], v[58:59], v[58:59], v[182:183]
	v_cvt_pk_bf16_f32 v60, v60, v61
	v_cvt_pk_bf16_f32 v61, v62, v63
	v_cvt_pk_bf16_f32 v62, v56, v57
	v_cvt_pk_bf16_f32 v63, v58, v59
	global_store_dwordx4 v[170:171], v[60:63], off offset:3072
	v_pk_mul_f32 v[52:53], v[52:53], v[180:181] op_sel_hi:[1,0]
	v_pk_mul_f32 v[54:55], v[54:55], v[180:181] op_sel_hi:[1,0]
	v_pk_mul_f32 v[48:49], v[48:49], v[180:181] op_sel_hi:[1,0]
	v_pk_mul_f32 v[50:51], v[50:51], v[180:181] op_sel_hi:[1,0]
	v_pk_fma_f32 v[182:183], v[52:53], v[52:53], v[182:183]
	v_pk_fma_f32 v[182:183], v[54:55], v[54:55], v[182:183]
	v_pk_fma_f32 v[182:183], v[48:49], v[48:49], v[182:183]
	v_pk_fma_f32 v[182:183], v[50:51], v[50:51], v[182:183]
	v_cvt_pk_bf16_f32 v52, v52, v53
	v_cvt_pk_bf16_f32 v53, v54, v55
	v_cvt_pk_bf16_f32 v54, v48, v49
	v_cvt_pk_bf16_f32 v55, v50, v51
	global_store_dwordx4 v[170:171], v[52:55], off offset:3328
	v_add_f32_e32 v184, v182, v183
	v_mov_b32_e32 v185, v184
	s_nop 1
	v_permlane32_swap_b32 v185, v184
	s_nop 1
	v_add_f32_e32 v184, v184, v185
	v_mov_b32_e32 v185, v184
	s_nop 1
	v_permlane16_swap_b32 v185, v184
	s_nop 1
	v_add_f32_e32 v184, v184, v185
	s_mov_b64 exec, s[46:47]
	global_atomic_add_f32 v[172:173], v184, off offset:512
	s_mov_b64 exec, -1
	s_mov_b64 vcc, 0x3000
	s_nop 0
	v_lshl_add_u64 v[170:171], v[170:171], 0, vcc
	s_waitcnt vmcnt(17)
	v_fmamk_f32 v180, v219, 0x3a800000, v194
	v_rsq_f32_e32 v180, v180
	s_nop 0
	v_pk_mul_f32 v[44:45], v[44:45], v[180:181] op_sel_hi:[1,0]
	v_pk_mul_f32 v[46:47], v[46:47], v[180:181] op_sel_hi:[1,0]
	v_pk_mul_f32 v[40:41], v[40:41], v[180:181] op_sel_hi:[1,0]
	v_pk_mul_f32 v[42:43], v[42:43], v[180:181] op_sel_hi:[1,0]
	v_pk_mul_f32 v[182:183], v[44:45], v[44:45]
	v_pk_fma_f32 v[182:183], v[46:47], v[46:47], v[182:183]
	v_pk_fma_f32 v[182:183], v[40:41], v[40:41], v[182:183]
	v_pk_fma_f32 v[182:183], v[42:43], v[42:43], v[182:183]
	v_cvt_pk_bf16_f32 v44, v44, v45
	v_cvt_pk_bf16_f32 v45, v46, v47
	v_cvt_pk_bf16_f32 v46, v40, v41
	v_cvt_pk_bf16_f32 v47, v42, v43
	global_store_dwordx4 v[170:171], v[44:47], off offset:3072
	v_pk_mul_f32 v[36:37], v[36:37], v[180:181] op_sel_hi:[1,0]
	v_pk_mul_f32 v[38:39], v[38:39], v[180:181] op_sel_hi:[1,0]
	v_pk_mul_f32 v[32:33], v[32:33], v[180:181] op_sel_hi:[1,0]
	v_pk_mul_f32 v[34:35], v[34:35], v[180:181] op_sel_hi:[1,0]
	v_pk_fma_f32 v[182:183], v[36:37], v[36:37], v[182:183]
	v_pk_fma_f32 v[182:183], v[38:39], v[38:39], v[182:183]
	v_pk_fma_f32 v[182:183], v[32:33], v[32:33], v[182:183]
	v_pk_fma_f32 v[182:183], v[34:35], v[34:35], v[182:183]
	v_cvt_pk_bf16_f32 v36, v36, v37
	v_cvt_pk_bf16_f32 v37, v38, v39
	v_cvt_pk_bf16_f32 v38, v32, v33
	v_cvt_pk_bf16_f32 v39, v34, v35
	global_store_dwordx4 v[170:171], v[36:39], off offset:3328
	v_add_f32_e32 v184, v182, v183
	v_mov_b32_e32 v185, v184
	s_nop 1
	v_permlane32_swap_b32 v185, v184
	s_nop 1
	v_add_f32_e32 v184, v184, v185
	v_mov_b32_e32 v185, v184
	s_nop 1
	v_permlane16_swap_b32 v185, v184
	s_nop 1
	v_add_f32_e32 v184, v184, v185
	s_mov_b64 exec, s[46:47]
	global_atomic_add_f32 v[172:173], v184, off offset:576
	s_mov_b64 exec, -1
	s_mov_b64 vcc, 0x3000
	s_nop 0
	v_lshl_add_u64 v[170:171], v[170:171], 0, vcc
	s_waitcnt vmcnt(19)
	v_fmamk_f32 v180, v220, 0x3a800000, v194
	v_rsq_f32_e32 v180, v180
	s_nop 0
	v_pk_mul_f32 v[28:29], v[28:29], v[180:181] op_sel_hi:[1,0]
	v_pk_mul_f32 v[30:31], v[30:31], v[180:181] op_sel_hi:[1,0]
	v_pk_mul_f32 v[24:25], v[24:25], v[180:181] op_sel_hi:[1,0]
	v_pk_mul_f32 v[26:27], v[26:27], v[180:181] op_sel_hi:[1,0]
	v_pk_mul_f32 v[182:183], v[28:29], v[28:29]
	v_pk_fma_f32 v[182:183], v[30:31], v[30:31], v[182:183]
	v_pk_fma_f32 v[182:183], v[24:25], v[24:25], v[182:183]
	v_pk_fma_f32 v[182:183], v[26:27], v[26:27], v[182:183]
	v_cvt_pk_bf16_f32 v28, v28, v29
	v_cvt_pk_bf16_f32 v29, v30, v31
	v_cvt_pk_bf16_f32 v30, v24, v25
	v_cvt_pk_bf16_f32 v31, v26, v27
	global_store_dwordx4 v[170:171], v[28:31], off offset:3072
	v_pk_mul_f32 v[20:21], v[20:21], v[180:181] op_sel_hi:[1,0]
	v_pk_mul_f32 v[22:23], v[22:23], v[180:181] op_sel_hi:[1,0]
	v_pk_mul_f32 v[16:17], v[16:17], v[180:181] op_sel_hi:[1,0]
	v_pk_mul_f32 v[18:19], v[18:19], v[180:181] op_sel_hi:[1,0]
	v_pk_fma_f32 v[182:183], v[20:21], v[20:21], v[182:183]
	v_pk_fma_f32 v[182:183], v[22:23], v[22:23], v[182:183]
	v_pk_fma_f32 v[182:183], v[16:17], v[16:17], v[182:183]
	v_pk_fma_f32 v[182:183], v[18:19], v[18:19], v[182:183]
	v_cvt_pk_bf16_f32 v20, v20, v21
	v_cvt_pk_bf16_f32 v21, v22, v23
	v_cvt_pk_bf16_f32 v22, v16, v17
	v_cvt_pk_bf16_f32 v23, v18, v19
	global_store_dwordx4 v[170:171], v[20:23], off offset:3328
	v_add_f32_e32 v184, v182, v183
	v_mov_b32_e32 v185, v184
	s_nop 1
	v_permlane32_swap_b32 v185, v184
	s_nop 1
	v_add_f32_e32 v184, v184, v185
	v_mov_b32_e32 v185, v184
	s_nop 1
	v_permlane16_swap_b32 v185, v184
	s_nop 1
	v_add_f32_e32 v184, v184, v185
	s_mov_b64 exec, s[46:47]
	global_atomic_add_f32 v[172:173], v184, off offset:640
	s_mov_b64 exec, -1
	s_mov_b64 vcc, 0x3000
	s_nop 0
	v_lshl_add_u64 v[170:171], v[170:171], 0, vcc
	s_waitcnt vmcnt(21)
	v_fmamk_f32 v180, v221, 0x3a800000, v194
	v_rsq_f32_e32 v180, v180
	s_nop 0
	v_pk_mul_f32 v[12:13], v[12:13], v[180:181] op_sel_hi:[1,0]
	v_pk_mul_f32 v[14:15], v[14:15], v[180:181] op_sel_hi:[1,0]
	v_pk_mul_f32 v[8:9], v[8:9], v[180:181] op_sel_hi:[1,0]
	v_pk_mul_f32 v[10:11], v[10:11], v[180:181] op_sel_hi:[1,0]
	v_pk_mul_f32 v[182:183], v[12:13], v[12:13]
	v_pk_fma_f32 v[182:183], v[14:15], v[14:15], v[182:183]
	v_pk_fma_f32 v[182:183], v[8:9], v[8:9], v[182:183]
	v_pk_fma_f32 v[182:183], v[10:11], v[10:11], v[182:183]
	v_cvt_pk_bf16_f32 v12, v12, v13
	v_cvt_pk_bf16_f32 v13, v14, v15
	v_cvt_pk_bf16_f32 v14, v8, v9
	v_cvt_pk_bf16_f32 v15, v10, v11
	global_store_dwordx4 v[170:171], v[12:15], off offset:3072
	v_pk_mul_f32 v[4:5], v[4:5], v[180:181] op_sel_hi:[1,0]
	v_pk_mul_f32 v[6:7], v[6:7], v[180:181] op_sel_hi:[1,0]
	v_pk_mul_f32 v[0:1], v[0:1], v[180:181] op_sel_hi:[1,0]
	v_pk_mul_f32 v[2:3], v[2:3], v[180:181] op_sel_hi:[1,0]
	v_pk_fma_f32 v[182:183], v[4:5], v[4:5], v[182:183]
	v_pk_fma_f32 v[182:183], v[6:7], v[6:7], v[182:183]
	v_pk_fma_f32 v[182:183], v[0:1], v[0:1], v[182:183]
	v_pk_fma_f32 v[182:183], v[2:3], v[2:3], v[182:183]
	v_cvt_pk_bf16_f32 v4, v4, v5
	v_cvt_pk_bf16_f32 v5, v6, v7
	v_cvt_pk_bf16_f32 v6, v0, v1
	v_cvt_pk_bf16_f32 v7, v2, v3
	global_store_dwordx4 v[170:171], v[4:7], off offset:3328
	v_add_f32_e32 v184, v182, v183
	v_mov_b32_e32 v185, v184
	s_nop 1
	v_permlane32_swap_b32 v185, v184
	s_nop 1
	v_add_f32_e32 v184, v184, v185
	v_mov_b32_e32 v185, v184
	s_nop 1
	v_permlane16_swap_b32 v185, v184
	s_nop 1
	v_add_f32_e32 v184, v184, v185
	s_mov_b64 exec, s[46:47]
	global_atomic_add_f32 v[172:173], v184, off offset:704
	s_mov_b64 exec, -1
	s_mov_b64 s[48:49], exec
	s_branch .LBB0_612
